# phase-0 small-weight transposes: done by workgroups 128-255 only (0-127 carry two modulation items), all of a thread's loads issued together and waited once
# baseline (speedup 1.0000x reference)
; #define LAS __attribute__((address_space(3)))
; __device__ __forceinline__ int ltid(int wvs) { int t = (wvs << 6) | (int)__builtin_amdgcn_mbcnt_hi(~0u, __builtin_amdgcn_mbcnt_lo(~0u, 0u)); asm volatile("" : "+v"(t)); return t; }
; __device__ __forceinline__ int lbid() { int b = __builtin_amdgcn_workgroup_id_x(); asm volatile("" : "+s"(b)); return b; }
; __device__ __forceinline__ void convert_weight(const int wvs, LAS unsigned char* lds, const float* src, hf* dst, int K, int Nsrc, int Ndst, bool wmap, int t0, int& tbase) {
;   LAS float* tl = (LAS float*)lds;
;   const int nkt = K / 64, nnt = Ndst / 64, ntiles = nkt * nnt, tid = ltid(wvs), ty = tid >> 6, tx = tid & 63;
;   int t = t0; while (t < tbase) t += NWG;
;   for (; t < tbase + ntiles; t += 4 * NWG) {
;     float v[4][8];
; #pragma unroll
;     for (int u = 0; u < 4; ++u) { const int tu = t + u * NWG; const bool ok = tu < tbase + ntiles; const int tt = ok ? tu - tbase : 0, kt = tt % nkt, ntl = tt / nkt, k0 = kt * 64, n0 = ntl * 64;
; __device__ __forceinline__ void phase0a(const int wvs, const Params& p, LAS unsigned char* lds) {
;     ...
;   { const int gt = lbid() * 512 + tid, gs = NWG * 512;
;     for (int l = 0; l < 2; ++l) { unsigned char* sb = p.ws + OFF_SMALL + (size_t)l * SZ_SMALL;
;       hf* gluT = (hf*)sb; hf* wupT = (hf*)(sb + SZ_GLUT); hf* aupT = (hf*)(sb + SZ_GLUT + SZ_WUPT); hf* gupT = (hf*)(sb + SZ_GLUT + 2 * SZ_WUPT);
;       for (int i = gt; i < 65536; i += gs) { const int n = i >> 8, k = i & 255; gluT[i] = (hf)p.in[I_GLUW][(size_t)l * 65536 + k * 256 + n]; }
;       for (int i = gt; i < 2 * 384 * 64; i += gs) { const int r = i & 63, n = (i >> 6) % 384, d = i / (384 * 64); const size_t si = ((size_t)(l * 2 + d) * 64 + r) * 384 + n;
;         wupT[i] = (hf)p.in[I_WUP][si]; aupT[i] = (hf)p.in[I_AUP][si]; }
;       for (int i = gt; i < 384 * 128; i += gs) { const int r = i & 127, n = i >> 7; gupT[i] = (hf)p.in[I_GUP][((size_t)l * 128 + r) * 384 + n]; }
;     }
.LBB0_27:
	s_mov_b32 s2, s28
	s_barrier
	s_sub_i32 s4, s28, 0x80
	s_cmp_lt_i32 s4, 0
	s_cbranch_scc1 .Lsmall_done
	s_add_u32 s2, s30, 0x1900000
	s_addc_u32 s3, s31, 0
	v_lshl_add_u32 v2, s4, 9, v193
	v_and_b32_e32 v3, 0xff, v2
	v_lshrrev_b32_e32 v4, 8, v2
	v_lshl_add_u32 v3, v3, 8, v4
	v_lshlrev_b32_e32 v3, 2, v3
	v_add_u32_e32 v4, 0x40000, v3
	global_load_dword v10, v3, s[18:19]
	global_load_dword v11, v4, s[18:19]
	s_cmpk_gt_i32 s4, 0x5f
	s_cbranch_scc1 .Lsmall_wait
	v_and_b32_e32 v5, 63, v2
	v_lshrrev_b32_e32 v6, 6, v2
	v_mov_b32_e32 v7, 0x5e80
	v_cmp_lt_u32_e32 vcc, 0x17f, v6
	v_mul_u32_u24_e32 v5, 0x180, v5
	s_nop 0
	v_cndmask_b32_e32 v7, 0, v7, vcc
	v_add3_u32 v5, v5, v6, v7
	v_lshlrev_b32_e32 v5, 2, v5
	v_add_u32_e32 v6, 0x30000, v5
	global_load_dword v12, v5, s[34:35]
	global_load_dword v13, v5, s[36:37]
	global_load_dword v14, v6, s[34:35]
	global_load_dword v15, v6, s[36:37]
	v_and_b32_e32 v7, 0x7f, v2
	v_lshrrev_b32_e32 v8, 7, v2
	v_mul_u32_u24_e32 v7, 0x180, v7
	v_add_lshl_u32 v7, v7, v8, 2
	v_add_u32_e32 v8, 0x30000, v7
	global_load_dword v16, v7, s[38:39]
	global_load_dword v17, v8, s[38:39]
.Lsmall_wait:
	v_lshlrev_b32_e32 v2, 1, v2
	v_add_u32_e32 v9, 0x68000, v2
	s_waitcnt vmcnt(0)
	v_cvt_f16_f32_e32 v10, v10
	v_cvt_f16_f32_e32 v11, v11
	global_store_short v2, v10, s[2:3]
	global_store_short v9, v11, s[2:3]
	s_cmpk_gt_i32 s4, 0x5f
	s_cbranch_scc1 .Lsmall_done
	v_cvt_f16_f32_e32 v12, v12
	v_cvt_f16_f32_e32 v13, v13
	v_cvt_f16_f32_e32 v14, v14
	v_cvt_f16_f32_e32 v15, v15
	v_cvt_f16_f32_e32 v16, v16
	v_cvt_f16_f32_e32 v17, v17
	v_add_u32_e32 v3, 0x20000, v2
	v_add_u32_e32 v4, 0x38000, v2
	v_add_u32_e32 v5, 0x50000, v2
	global_store_short v3, v12, s[2:3]
	global_store_short v4, v13, s[2:3]
	global_store_short v5, v16, s[2:3]
	v_add_u32_e32 v3, 0x68000, v3
	v_add_u32_e32 v4, 0x68000, v4
	v_add_u32_e32 v5, 0x68000, v5
	global_store_short v3, v14, s[2:3]
	global_store_short v4, v15, s[2:3]
	global_store_short v5, v17, s[2:3]
.Lsmall_done:
	s_mov_b64 s[8:9], s[0:1]
	s_mov_b32 s18, s28
	s_load_dwordx4 s[4:7], s[8:9], 0x48
	s_load_dwordx2 s[2:3], s[8:9], 0x138
	s_max_i32 s8, s18, 0
	s_sub_i32 s8, s8, s18
	s_addk_i32 s8, 0xff
	s_and_b32 s9, s8, 0xffffff00
	s_add_i32 s20, s9, s18
	v_mov_b32_e32 v2, v193
	s_cmpk_gt_i32 s20, 0x37f
	s_movk_i32 s19, 0xff
	s_cbranch_scc1 .LBB0_170
	v_and_b32_e32 v9, 63, v2
	v_ashrrev_i32_e32 v8, 6, v2
	s_movk_i32 s9, 0x104
	v_lshlrev_b32_e32 v2, 1, v9
	v_mov_b32_e32 v3, 0
	s_lshl_b32 s8, s8, 6
	v_lshl_add_u32 v6, v8, 2, 0
	v_lshl_add_u32 v7, v9, 2, 0
	v_mul_u32_u24_e32 v11, 0x104, v9
	s_waitcnt lgkmcnt(0)
	v_lshl_add_u64 v[4:5], s[2:3], 0, v[2:3]
	v_mul_lo_u32 v2, v8, s9
	s_and_b32 s8, s8, 0xffffc000
	s_lshl_b32 s9, s18, 6
	s_add_i32 s21, s8, s9
	s_movk_i32 s22, 0x718
	s_movk_i32 s23, 0x3460
	v_add_u32_e32 v10, v7, v2
	s_movk_i32 s24, 0x4000
	s_mov_b32 s25, 0x8000
	s_mov_b32 s26, 0xc000
	s_mov_b32 s27, 0x10000
	s_mov_b32 s29, 0x14000
	v_add_u32_e32 v11, v6, v11
	s_branch .LBB0_76
